# SchedA start stagger: WG groups (c>>3)&3 delayed by g*1.5us so the per-unit gate-load bursts of the groups do not collide
# baseline (speedup 1.0000x reference)
.LBB0_794:
	s_or_b64 exec, exec, s[2:3]
	s_add_u32 s9, s26, 0xb9a0000
	s_addc_u32 s31, s27, 0
	s_add_u32 s12, s26, 0xca20000
	s_addc_u32 s13, s27, 0
	v_mov_b32_e32 v10, v0
	s_cmpk_lt_i32 s8, 0x400
	s_waitcnt lgkmcnt(0)
	s_barrier
	s_cselect_b64 s[16:17], -1, 0
	s_cmpk_gt_i32 s8, 0x3ff
	v_readfirstlane_b32 s50, v10
	s_cbranch_scc1 .LBB0_824
	s_lshr_b32 s0, s8, 3
	s_and_b32 s0, s0, 3
	s_cmp_eq_u32 s0, 0
	s_cbranch_scc1 .Lstag_done_sa
.Lstag_loop_sa:
	s_sleep 56
	s_sub_u32 s0, s0, 1
	s_cmp_lg_u32 s0, 0
	s_cbranch_scc1 .Lstag_loop_sa
.Lstag_done_sa:
	s_ashr_i32 s0, s8, 31
	s_lshr_b32 s0, s0, 29
	s_add_i32 s10, s8, s0
	s_and_b32 s0, s10, -8
	s_sub_i32 s0, s8, s0
	s_cmp_gt_i32 s0, -1
	s_cbranch_scc0 .LBB0_797
	s_lshl_b32 s11, s0, 7
	s_cbranch_execz .LBB0_798
	s_branch .LBB0_799
